# P1 side job second stream (cached rope-key rows to bf16): 16-chunk pass in front of its 8-chunk loop
# speedup vs baseline: 1.0036x; 1.0036x over previous
.LBB0_585:
	s_or_b64 exec, exec, s[8:9]
	s_mov_b64 s[0:1], 0x100000
	v_cmp_gt_u64_e32 vcc, s[0:1], v[6:7]
	s_and_saveexec_b64 s[8:9], vcc
	s_cbranch_execz .LBB0_589
	s_load_dwordx16 s[12:27], s[62:63], 0x0
	s_lshl_b64 s[0:1], s[6:7], 13
	v_lshlrev_b32_e32 v8, 4, v0
	v_mov_b32_e32 v9, 0
	v_mov_b32_e32 v5, v9
	s_waitcnt lgkmcnt(0)
	s_add_u32 s0, s24, s0
	s_addc_u32 s1, s25, s1
	v_lshl_add_u64 v[6:7], s[0:1], 0, v[8:9]
	s_lshl_b64 s[0:1], s[6:7], 12
	s_add_u32 s0, s34, s0
	s_addc_u32 s1, s35, s1
	v_lshl_add_u64 v[4:5], s[0:1], 0, v[4:5]
	s_mov_b64 s[0:1], 0x1ad00000
	v_lshl_add_u64 v[4:5], v[4:5], 0, s[0:1]
	s_mov_b64 s[6:7], 0
	s_mov_b32 s0, 0xf0000
	s_mov_b32 s1, 0x1e0000
	s_mov_b32 s2, 0x2d0000
	s_mov_b32 s3, 0x78000
	s_mov_b32 s4, 0x168000
	s_mov_b32 s5, 0x258000
	s_mov_b64 s[10:11], 0x78000
	s_mov_b64 s[12:13], 0x780000
	s_mov_b64 s[14:15], 0x3c0000
	s_mov_b64 s[18:19], 0xe1000
	s_mov_b64 s[20:21], 0xfffff
	s_mov_b64 s[42:43], 0xf0000
	s_mov_b64 s[44:45], 0x78000
	s_mov_b64 s[46:47], 0xf00000
	s_mov_b64 s[48:49], 0x69000
	s_mov_b64 s[50:51], 0x100000
	s_mov_b64 s[40:41], exec
	v_lshl_add_u64 v[60:61], v[2:3], 0, s[18:19]
	v_cmp_ge_u64_e32 vcc, s[20:21], v[60:61]
	s_and_b64 exec, exec, vcc
	s_cbranch_execz .Lcvb16_done
.Lcvb16_loop:
	global_load_dwordx4 v[64:67], v[6:7], off nt
	v_lshl_add_u64 v[62:63], v[6:7], 0, s[42:43]
	global_load_dwordx4 v[68:71], v[62:63], off nt
	v_lshl_add_u64 v[62:63], v[62:63], 0, s[42:43]
	global_load_dwordx4 v[72:75], v[62:63], off nt
	v_lshl_add_u64 v[62:63], v[62:63], 0, s[42:43]
	global_load_dwordx4 v[76:79], v[62:63], off nt
	v_lshl_add_u64 v[62:63], v[62:63], 0, s[42:43]
	global_load_dwordx4 v[80:83], v[62:63], off nt
	v_lshl_add_u64 v[62:63], v[62:63], 0, s[42:43]
	global_load_dwordx4 v[84:87], v[62:63], off nt
	v_lshl_add_u64 v[62:63], v[62:63], 0, s[42:43]
	global_load_dwordx4 v[88:91], v[62:63], off nt
	v_lshl_add_u64 v[62:63], v[62:63], 0, s[42:43]
	global_load_dwordx4 v[92:95], v[62:63], off nt
	v_lshl_add_u64 v[62:63], v[62:63], 0, s[42:43]
	global_load_dwordx4 v[96:99], v[62:63], off nt
	v_lshl_add_u64 v[62:63], v[62:63], 0, s[42:43]
	global_load_dwordx4 v[100:103], v[62:63], off nt
	v_lshl_add_u64 v[62:63], v[62:63], 0, s[42:43]
	global_load_dwordx4 v[104:107], v[62:63], off nt
	v_lshl_add_u64 v[62:63], v[62:63], 0, s[42:43]
	global_load_dwordx4 v[108:111], v[62:63], off nt
	v_lshl_add_u64 v[62:63], v[62:63], 0, s[42:43]
	global_load_dwordx4 v[112:115], v[62:63], off nt
	v_lshl_add_u64 v[62:63], v[62:63], 0, s[42:43]
	global_load_dwordx4 v[116:119], v[62:63], off nt
	v_lshl_add_u64 v[62:63], v[62:63], 0, s[42:43]
	global_load_dwordx4 v[120:123], v[62:63], off nt
	v_lshl_add_u64 v[62:63], v[62:63], 0, s[42:43]
	global_load_dwordx4 v[124:127], v[62:63], off nt
	s_waitcnt vmcnt(15)
	v_cvt_pk_bf16_f32 v64, v64, v65
	v_cvt_pk_bf16_f32 v65, v66, v67
	global_store_dwordx2 v[4:5], v[64:65], off
	s_waitcnt vmcnt(15)
	v_cvt_pk_bf16_f32 v68, v68, v69
	v_cvt_pk_bf16_f32 v69, v70, v71
	v_lshl_add_u64 v[62:63], v[4:5], 0, s[44:45]
	global_store_dwordx2 v[62:63], v[68:69], off
	s_waitcnt vmcnt(15)
	v_cvt_pk_bf16_f32 v72, v72, v73
	v_cvt_pk_bf16_f32 v73, v74, v75
	v_lshl_add_u64 v[62:63], v[62:63], 0, s[44:45]
	global_store_dwordx2 v[62:63], v[72:73], off
	s_waitcnt vmcnt(15)
	v_cvt_pk_bf16_f32 v76, v76, v77
	v_cvt_pk_bf16_f32 v77, v78, v79
	v_lshl_add_u64 v[62:63], v[62:63], 0, s[44:45]
	global_store_dwordx2 v[62:63], v[76:77], off
	s_waitcnt vmcnt(15)
	v_cvt_pk_bf16_f32 v80, v80, v81
	v_cvt_pk_bf16_f32 v81, v82, v83
	v_lshl_add_u64 v[62:63], v[62:63], 0, s[44:45]
	global_store_dwordx2 v[62:63], v[80:81], off
	s_waitcnt vmcnt(15)
	v_cvt_pk_bf16_f32 v84, v84, v85
	v_cvt_pk_bf16_f32 v85, v86, v87
	v_lshl_add_u64 v[62:63], v[62:63], 0, s[44:45]
	global_store_dwordx2 v[62:63], v[84:85], off
	s_waitcnt vmcnt(15)
	v_cvt_pk_bf16_f32 v88, v88, v89
	v_cvt_pk_bf16_f32 v89, v90, v91
	v_lshl_add_u64 v[62:63], v[62:63], 0, s[44:45]
	global_store_dwordx2 v[62:63], v[88:89], off
	s_waitcnt vmcnt(15)
	v_cvt_pk_bf16_f32 v92, v92, v93
	v_cvt_pk_bf16_f32 v93, v94, v95
	v_lshl_add_u64 v[62:63], v[62:63], 0, s[44:45]
	global_store_dwordx2 v[62:63], v[92:93], off
	s_waitcnt vmcnt(15)
	v_cvt_pk_bf16_f32 v96, v96, v97
	v_cvt_pk_bf16_f32 v97, v98, v99
	v_lshl_add_u64 v[62:63], v[62:63], 0, s[44:45]
	global_store_dwordx2 v[62:63], v[96:97], off
	s_waitcnt vmcnt(15)
	v_cvt_pk_bf16_f32 v100, v100, v101
	v_cvt_pk_bf16_f32 v101, v102, v103
	v_lshl_add_u64 v[62:63], v[62:63], 0, s[44:45]
	global_store_dwordx2 v[62:63], v[100:101], off
	s_waitcnt vmcnt(15)
	v_cvt_pk_bf16_f32 v104, v104, v105
	v_cvt_pk_bf16_f32 v105, v106, v107
	v_lshl_add_u64 v[62:63], v[62:63], 0, s[44:45]
	global_store_dwordx2 v[62:63], v[104:105], off
	s_waitcnt vmcnt(15)
	v_cvt_pk_bf16_f32 v108, v108, v109
	v_cvt_pk_bf16_f32 v109, v110, v111
	v_lshl_add_u64 v[62:63], v[62:63], 0, s[44:45]
	global_store_dwordx2 v[62:63], v[108:109], off
	s_waitcnt vmcnt(15)
	v_cvt_pk_bf16_f32 v112, v112, v113
	v_cvt_pk_bf16_f32 v113, v114, v115
	v_lshl_add_u64 v[62:63], v[62:63], 0, s[44:45]
	global_store_dwordx2 v[62:63], v[112:113], off
	s_waitcnt vmcnt(15)
	v_cvt_pk_bf16_f32 v116, v116, v117
	v_cvt_pk_bf16_f32 v117, v118, v119
	v_lshl_add_u64 v[62:63], v[62:63], 0, s[44:45]
	global_store_dwordx2 v[62:63], v[116:117], off
	s_waitcnt vmcnt(15)
	v_cvt_pk_bf16_f32 v120, v120, v121
	v_cvt_pk_bf16_f32 v121, v122, v123
	v_lshl_add_u64 v[62:63], v[62:63], 0, s[44:45]
	global_store_dwordx2 v[62:63], v[120:121], off
	s_waitcnt vmcnt(15)
	v_cvt_pk_bf16_f32 v124, v124, v125
	v_cvt_pk_bf16_f32 v125, v126, v127
	v_lshl_add_u64 v[62:63], v[62:63], 0, s[44:45]
	global_store_dwordx2 v[62:63], v[124:125], off
	v_lshl_add_u64 v[6:7], v[6:7], 0, s[46:47]
	v_lshl_add_u64 v[4:5], v[4:5], 0, s[12:13]
	v_lshl_add_u64 v[2:3], v[2:3], 0, s[42:43]
	v_lshl_add_u64 v[60:61], v[2:3], 0, s[18:19]
	v_cmp_ge_u64_e32 vcc, s[20:21], v[60:61]
	s_and_b64 exec, exec, vcc
	s_cbranch_execnz .Lcvb16_loop
.Lcvb16_done:
	s_mov_b64 exec, s[40:41]
	v_lshl_add_u64 v[60:61], v[2:3], 0, s[48:49]
	v_cmp_gt_u64_e32 vcc, s[50:51], v[60:61]
	s_and_b64 exec, exec, vcc
	s_cbranch_execz .LBB0_589
